# mix phase work queue: memory-bound gating items interleaved 1:1 with compute-bound attention items instead of run after them
# baseline (speedup 1.0000x reference)
; #define LAS __attribute__((address_space(3)))
; #define OPQV(x) asm volatile("" : "+v"(x))
; DEV void sgu_item(LAS unsigned char* lds, const bf16_t* P, const bf16_t* VN, const float* sgu_w, const float* sgu_b, bf16_t* OC, int item) {
;     int tid = threadIdx.x; OPQV(tid); const int lane = tid & 63, wv = tid >> 6, fr = lane & 15, g4 = lane >> 4;
;     LAS bf16_t* VT = (LAS bf16_t*)lds;
;     const int g = item & 7, ch = (item >> 3) & 15, b = item >> 7;
;     const size_t tok0 = (size_t)b * S_ + ch * 128;
;     const int t = wv * 16 + fr;
;     const size_t tok = tok0 + t;
;     u32x4 vin[4];
; #pragma unroll
;     for (int it = 0; it < 4; ++it) { const int idx = it * 512 + tid, s = idx >> 4, c8 = (idx & 15) * 8; vin[it] = *(const u32x4*)(VN + (tok0 + s) * 1024 + g * 128 + c8); }
;     const float* wrow = sgu_w + ((size_t)g * 128 + t) * 128;
;     f32x4 wa[4], wb[4];
; #pragma unroll
;     for (int ks = 0; ks < 4; ++ks) { wa[ks] = *(const f32x4*)(wrow + ks * 32 + g4 * 8); wb[ks] = *(const f32x4*)(wrow + ks * 32 + g4 * 8 + 4); }
;     u32x2 uu[8];
; #pragma unroll
;     for (int n = 0; n < 8; ++n) uu[n] = *(const u32x2*)(P + tok * NP + COL_U + g * 128 + n * 16 + g4 * 4);
;     const float bias = sgu_b[g * 128 + t];
; #pragma unroll
;     for (int it = 0; it < 4; ++it) { const int idx = it * 512 + tid, s = idx >> 4, c8 = (idx & 15) * 8;
; #pragma unroll
;         for (int j = 0; j < 4; ++j) { VT[(c8 + 2 * j) * 136 + s] = (bf16_t)(vin[it][j] & 0xffffu); VT[(c8 + 2 * j + 1) * 136 + s] = (bf16_t)(vin[it][j] >> 16); } }
; DEV void phase_mix(LAS unsigned char* lds, const bf16_t* P, const bf16_t* QB, const bf16_t* KV, const bf16_t* KC, const bf16_t* VC, const float* rel_bias, bf16_t* OB,
;                    const bf16_t* VN, const float* sgu_w, const float* sgu_b, bf16_t* OC, int* ctr) {
;     ...
;     for (;;) {
;         if (tid == 0) *(LAS int*)(lds + AT_NEXT) = atomicAdd(ctr, 1);
;         __syncthreads();
;         const int i = *(const LAS int*)(lds + AT_NEXT);
;         __syncthreads();
;         if (i >= 2048) break;
;         if (i < 1024) attn_item(lds, P, QB, KV, KC, VC, rel_bias, OB, (i & 31) >> 2, i & 3, 31 - (i >> 5));
;         else sgu_item(lds, P, VN, sgu_w, sgu_b, OC, i - 1024);
.LBB0_164:
	s_or_b64 exec, exec, s[4:5]
	v_mov_b32_e32 v0, s95
	s_waitcnt lgkmcnt(0)
	s_barrier
	ds_read_b32 v0, v0
	s_movk_i32 s4, 0x7ff
	s_waitcnt lgkmcnt(0)
	s_barrier
	v_cmp_lt_i32_e32 vcc, s4, v0
	v_readfirstlane_b32 s43, v0
	s_mov_b64 s[4:5], -1
	s_cbranch_vccnz .LBB0_159
	s_and_b32 vcc_lo, s43, 1
	s_lshr_b32 s43, s43, 1
	s_lshl_b32 vcc_lo, vcc_lo, 10
	s_or_b32 s43, s43, vcc_lo
	s_cmpk_gt_i32 s43, 0x3ff
	s_cbranch_scc0 .LBB0_167
	s_add_i32 s4, s43, 0xfffffc00
	s_lshl_b32 s5, s4, 4
	s_lshl_b32 s4, s4, 7
	v_mov_b32_e32 v8, v210
	s_and_b32 s6, s4, 0x380
	s_and_b32 s36, s5, 0x3f80
	v_lshlrev_b32_e32 v0, 3, v8
	s_lshl_b32 s4, s6, 1
	v_and_b32_e32 v9, 0x78, v0
	s_add_u32 s44, s34, s4
	v_ashrrev_i32_e32 v4, 4, v8
	s_addc_u32 s45, s35, 0
	v_lshlrev_b32_e32 v0, 1, v9
	v_ashrrev_i32_e32 v5, 31, v4
	v_lshl_add_u64 v[2:3], s[44:45], 0, v[0:1]
	v_lshl_add_u64 v[6:7], v[4:5], 0, s[36:37]
	v_add_u32_e32 v0, 0x200, v8
	v_lshlrev_b64 v[6:7], 11, v[6:7]
	v_ashrrev_i32_e32 v70, 4, v0
	v_lshl_add_u64 v[6:7], v[2:3], 0, v[6:7]
	v_ashrrev_i32_e32 v71, 31, v70
	global_load_dwordx4 v[30:33], v[6:7], off
	v_lshl_add_u64 v[6:7], v[70:71], 0, s[36:37]
	v_add_u32_e32 v0, 0x400, v8
	v_lshlrev_b64 v[6:7], 11, v[6:7]
	v_ashrrev_i32_e32 v72, 4, v0
	v_lshl_add_u64 v[6:7], v[2:3], 0, v[6:7]
	v_ashrrev_i32_e32 v73, 31, v72
	global_load_dwordx4 v[34:37], v[6:7], off
	v_lshl_add_u64 v[6:7], v[72:73], 0, s[36:37]
	v_add_u32_e32 v0, 0x600, v8
	v_lshlrev_b64 v[6:7], 11, v[6:7]
	v_ashrrev_i32_e32 v74, 4, v0
	v_lshl_add_u64 v[6:7], v[2:3], 0, v[6:7]
	v_ashrrev_i32_e32 v75, 31, v74
	global_load_dwordx4 v[38:41], v[6:7], off
	v_lshl_add_u64 v[6:7], v[74:75], 0, s[36:37]
	v_ashrrev_i32_e32 v0, 2, v8
	v_lshlrev_b64 v[6:7], 11, v[6:7]
	s_waitcnt vmcnt(11)
	v_bfi_b32 v28, -16, v0, v8
	v_lshl_add_u64 v[2:3], v[2:3], 0, v[6:7]
	v_ashrrev_i32_e32 v29, 31, v28
	s_mov_b32 s7, s37
	global_load_dwordx4 v[42:45], v[2:3], off
	v_lshl_add_u64 v[2:3], v[28:29], 0, s[6:7]
	v_bfe_u32 v0, v8, 4, 2
	v_lshlrev_b64 v[2:3], 9, v[2:3]
	v_lshl_add_u64 v[2:3], s[80:81], 0, v[2:3]
	v_lshlrev_b32_e32 v6, 5, v0
	v_mov_b32_e32 v7, v1
	v_lshl_add_u64 v[6:7], v[2:3], 0, v[6:7]
	global_load_dwordx4 v[46:49], v[6:7], off
	global_load_dwordx4 v[50:53], v[6:7], off offset:16
	v_mov_b64_e32 v[2:3], s[76:77]
	v_and_b32_e32 v82, 15, v8
	v_add_u32_e32 v8, s6, v28
	s_movk_i32 s6, 0x110
	v_lshl_add_u64 v[24:25], v[28:29], 0, s[36:37]
	s_mov_b32 s5, s37
	v_mad_u32_u24 v71, v9, s6, 0
	v_ashrrev_i32_e32 v9, 31, v8
	v_mad_i64_i32 v[2:3], s[6:7], v24, s59, v[2:3]
	v_lshl_add_u32 v73, v4, 1, v71
	v_lshlrev_b32_e32 v0, 3, v0
	v_lshl_add_u64 v[4:5], v[8:9], 2, s[82:83]
	v_lshl_add_u64 v[2:3], v[2:3], 0, s[4:5]
	global_load_dword v29, v[4:5], off
	v_lshl_add_u64 v[10:11], v[2:3], 0, v[0:1]
	global_load_dwordx4 v[54:57], v[6:7], off offset:144
	global_load_dwordx4 v[58:61], v[6:7], off offset:128
	global_load_dwordx4 v[62:65], v[6:7], off offset:272
	global_load_dwordx4 v[66:69], v[6:7], off offset:256
	global_load_dwordx4 v[2:5], v[6:7], off offset:400
	s_nop 0
	global_load_dwordx4 v[6:9], v[6:7], off offset:384
	s_mov_b64 s[6:7], 0x2c00
	s_movk_i32 s5, 0x2000
	v_lshl_add_u64 v[76:77], v[10:11], 0, s[6:7]
	v_add_co_u32_e32 v10, vcc, s5, v10
	v_or_b32_e32 v90, 32, v0
	s_nop 0
	v_addc_co_u32_e32 v11, vcc, 0, v11, vcc
	global_load_dwordx2 v[22:23], v[76:77], off offset:32
	global_load_dwordx2 v[20:21], v[76:77], off offset:64
	global_load_dwordx2 v[18:19], v[76:77], off offset:96
	global_load_dwordx2 v[16:17], v[76:77], off offset:128
	global_load_dwordx2 v[26:27], v[10:11], off offset:3072
	global_load_dwordx2 v[14:15], v[76:77], off offset:160
	global_load_dwordx2 v[12:13], v[76:77], off offset:192
	s_nop 0
	global_load_dwordx2 v[10:11], v[76:77], off offset:224
	v_cmp_le_i32_e32 vcc, v0, v28
	v_or_b32_e32 v91, 33, v0
	s_movk_i32 s5, 0x88
	v_mad_u32_u24 v83, v82, s5, v227
	v_mad_u32_u24 v84, v82, s5, v252
	v_mad_u32_u24 v85, v82, s5, v216
	v_mad_u32_u24 v86, v82, s5, v217
	v_mad_u32_u24 v87, v82, s5, v218
	s_waitcnt vmcnt(20)
	ds_write_b16 v73, v30
	ds_write_b16_d16_hi v73, v30 offset:272
	ds_write_b16 v73, v31 offset:544
	ds_write_b16_d16_hi v73, v31 offset:816
	ds_write_b16 v73, v32 offset:1088
	ds_write_b16_d16_hi v73, v32 offset:1360
	ds_write_b16 v73, v33 offset:1632
	ds_write_b16_d16_hi v73, v33 offset:1904
	v_lshl_add_u32 v30, v70, 1, v71
	s_waitcnt vmcnt(19)
	ds_write_b16 v30, v34
	ds_write_b16_d16_hi v30, v34 offset:272
	ds_write_b16 v30, v35 offset:544
	ds_write_b16_d16_hi v30, v35 offset:816
	ds_write_b16 v30, v36 offset:1088
	ds_write_b16_d16_hi v30, v36 offset:1360
	ds_write_b16 v30, v37 offset:1632
	ds_write_b16_d16_hi v30, v37 offset:1904
	v_lshl_add_u32 v30, v72, 1, v71
	s_waitcnt vmcnt(18)
	ds_write_b16 v30, v38
	ds_write_b16_d16_hi v30, v38 offset:272
	ds_write_b16 v30, v39 offset:544
	ds_write_b16_d16_hi v30, v39 offset:816
	ds_write_b16 v30, v40 offset:1088
	ds_write_b16_d16_hi v30, v40 offset:1360
	ds_write_b16 v30, v41 offset:1632
	ds_write_b16_d16_hi v30, v41 offset:1904
	v_lshl_add_u32 v30, v74, 1, v71
	s_waitcnt vmcnt(17)
	ds_write_b16 v30, v42
	ds_write_b16_d16_hi v30, v42 offset:272
	ds_write_b16 v30, v43 offset:544
	ds_write_b16_d16_hi v30, v43 offset:816
	ds_write_b16 v30, v44 offset:1088
	ds_write_b16_d16_hi v30, v44 offset:1360
	ds_write_b16 v30, v45 offset:1632
	ds_write_b16_d16_hi v30, v45 offset:1904
	v_or_b32_e32 v32, 2, v0
	v_or_b32_e32 v33, 3, v0
	v_or_b32_e32 v34, 4, v0
	v_or_b32_e32 v35, 5, v0
	v_or_b32_e32 v36, 6, v0
	v_or_b32_e32 v37, 7, v0
	s_waitcnt vmcnt(16) lgkmcnt(0)
	v_cndmask_b32_e32 v30, 0, v46, vcc
	v_cmp_lt_i32_e32 vcc, v0, v28
	s_barrier
; #define LAS __attribute__((address_space(3)))
; DEV u32x4 pack8(const float (&f)[8]) { u32x4 w; w.x = cvt_pk_bf16(f[0], f[1]); w.y = cvt_pk_bf16(f[2], f[3]); w.z = cvt_pk_bf16(f[4], f[5]); w.w = cvt_pk_bf16(f[6], f[7]); return w; }
; DEV void sgu_item(LAS unsigned char* lds, const bf16_t* P, const bf16_t* VN, const float* sgu_w, const float* sgu_b, bf16_t* OC, int item) {
;     ...
; #pragma unroll
;     for (int ks = 0; ks < 4; ++ks) { const int s0 = ks * 32 + g4 * 8;
;         float wf[8] = {wa[ks][0], wa[ks][1], wa[ks][2], wa[ks][3], wb[ks][0], wb[ks][1], wb[ks][2], wb[ks][3]};
; #pragma unroll
;         for (int j = 0; j < 8; ++j) if (s0 + j > t) wf[j] = 0.f;
;         const bf16x8 wfr = as_bf16x8(pack8(wf));
; #pragma unroll
;         for (int n = 0; n < 8; ++n) { const bf16x8 vf = *(const LAS bf16x8*)(lds + ((n * 16 + fr) * 136 + s0) * 2);
;             acc[n] = __builtin_amdgcn_mfma_f32_16x16x32_bf16(vf, wfr, acc[n], 0, 0, 0); } }
	s_nop 0
	v_cndmask_b32_e32 v31, 0, v47, vcc
	v_cmp_le_i32_e32 vcc, v32, v28
	v_cvt_pk_bf16_f32 v30, v30, v31
	v_mad_u32_u24 v88, v82, s5, v219
	v_mad_u32_u24 v89, v82, s5, v220
	v_cndmask_b32_e32 v32, 0, v48, vcc
	v_cmp_le_i32_e32 vcc, v33, v28
	v_add_u32_e32 v38, v83, v0
	v_add_u32_e32 v42, v84, v0
	v_cndmask_b32_e32 v33, 0, v49, vcc
	v_cmp_le_i32_e32 vcc, v34, v28
	v_cvt_pk_bf16_f32 v31, v32, v33
	v_add_u32_e32 v46, v85, v0
	v_add_u32_e32 v70, v87, v0
	s_waitcnt vmcnt(15)
	v_cndmask_b32_e32 v34, 0, v50, vcc
	v_cmp_le_i32_e32 vcc, v35, v28
	v_add_u32_e32 v50, v86, v0
	v_add_u32_e32 v74, v88, v0
	v_cndmask_b32_e32 v35, 0, v51, vcc
	v_cmp_le_i32_e32 vcc, v36, v28
	v_cvt_pk_bf16_f32 v32, v34, v35
	v_mad_u32_u24 v34, v82, s5, v0
	v_lshl_add_u32 v34, v34, 1, 0
	v_cndmask_b32_e32 v36, 0, v52, vcc
	v_cmp_le_i32_e32 vcc, v37, v28
	v_add_u32_e32 v78, v89, v0
	v_lshl_add_u32 v38, v38, 1, 0
	v_cndmask_b32_e32 v37, 0, v53, vcc
	v_cmp_le_i32_e32 vcc, v90, v28
	v_cvt_pk_bf16_f32 v33, v36, v37
	ds_read_b128 v[34:37], v34
	ds_read_b128 v[38:41], v38
	s_waitcnt vmcnt(12)
	v_cndmask_b32_e32 v58, 0, v58, vcc
	v_cmp_le_i32_e32 vcc, v91, v28
	v_or_b32_e32 v91, 34, v0
	v_lshl_add_u32 v42, v42, 1, 0
	v_cndmask_b32_e32 v59, 0, v59, vcc
	v_cmp_le_i32_e32 vcc, v91, v28
	v_or_b32_e32 v91, 35, v0
	v_lshl_add_u32 v46, v46, 1, 0
	v_cndmask_b32_e32 v60, 0, v60, vcc
	v_cmp_le_i32_e32 vcc, v91, v28
	v_or_b32_e32 v91, 36, v0
	v_lshl_add_u32 v50, v50, 1, 0
	v_cndmask_b32_e32 v61, 0, v61, vcc
	v_cmp_le_i32_e32 vcc, v91, v28
	v_lshl_add_u32 v70, v70, 1, 0
	v_lshl_add_u32 v74, v74, 1, 0
	v_cndmask_b32_e32 v91, 0, v54, vcc
	v_or_b32_e32 v54, 37, v0
	v_cmp_le_i32_e32 vcc, v54, v28
	v_or_b32_e32 v54, 38, v0
	v_lshl_add_u32 v78, v78, 1, 0
	v_cndmask_b32_e32 v92, 0, v55, vcc
	v_cmp_le_i32_e32 vcc, v54, v28
	v_or_b32_e32 v54, 39, v0
	ds_read_b128 v[42:45], v42
	ds_read_b128 v[46:49], v46
	ds_read_b128 v[50:53], v50
	ds_read_b128 v[70:73], v70
	ds_read_b128 v[74:77], v74
	ds_read_b128 v[78:81], v78
	v_cndmask_b32_e32 v93, 0, v56, vcc
	v_cmp_le_i32_e32 vcc, v54, v28
	v_cvt_pk_bf16_f32 v54, v58, v59
	v_mad_u32_u24 v58, v82, s5, v90
	v_lshl_add_u32 v58, v58, 1, 0
	v_cndmask_b32_e32 v57, 0, v57, vcc
	v_cvt_pk_bf16_f32 v55, v60, v61
	v_cvt_pk_bf16_f32 v56, v91, v92
	v_cvt_pk_bf16_f32 v57, v93, v57
	ds_read_b128 v[58:61], v58
	s_waitcnt lgkmcnt(8)
	v_mfma_f32_16x16x32_bf16 v[34:37], v[34:37], v[30:33], 0
	v_lshlrev_b64 v[24:25], 11, v[24:25]
	v_lshl_add_u64 v[24:25], s[88:89], 0, v[24:25]
	s_waitcnt lgkmcnt(7)
	v_mfma_f32_16x16x32_bf16 v[38:41], v[38:41], v[30:33], 0
	s_waitcnt lgkmcnt(6)
	v_mfma_f32_16x16x32_bf16 v[42:45], v[42:45], v[30:33], 0
	s_waitcnt lgkmcnt(5)
	v_mfma_f32_16x16x32_bf16 v[46:49], v[46:49], v[30:33], 0
	s_waitcnt lgkmcnt(4)
	v_mfma_f32_16x16x32_bf16 v[50:53], v[50:53], v[30:33], 0
	s_waitcnt lgkmcnt(3)
	v_mfma_f32_16x16x32_bf16 v[70:73], v[70:73], v[30:33], 0
	s_waitcnt lgkmcnt(2)
	v_mfma_f32_16x16x32_bf16 v[74:77], v[74:77], v[30:33], 0
	s_waitcnt lgkmcnt(1)
	v_mfma_f32_16x16x32_bf16 v[30:33], v[78:81], v[30:33], 0
	v_add_u32_e32 v78, v90, v83
	v_lshl_add_u32 v78, v78, 1, 0
	ds_read_b128 v[78:81], v78
	s_waitcnt lgkmcnt(1)
	v_mfma_f32_16x16x32_bf16 v[34:37], v[58:61], v[54:57], v[34:37]
	v_add_u32_e32 v58, v90, v84
	v_lshl_add_u32 v58, v58, 1, 0
	ds_read_b128 v[58:61], v58
	s_waitcnt lgkmcnt(1)
	v_mfma_f32_16x16x32_bf16 v[38:41], v[78:81], v[54:57], v[38:41]
	v_add_u32_e32 v78, v90, v85
	v_lshl_add_u32 v78, v78, 1, 0
	ds_read_b128 v[78:81], v78
	s_waitcnt lgkmcnt(1)
	v_mfma_f32_16x16x32_bf16 v[42:45], v[58:61], v[54:57], v[42:45]
	v_add_u32_e32 v58, v90, v86
	v_lshl_add_u32 v58, v58, 1, 0
	ds_read_b128 v[58:61], v58
	s_waitcnt lgkmcnt(1)
	v_mfma_f32_16x16x32_bf16 v[46:49], v[78:81], v[54:57], v[46:49]
	v_add_u32_e32 v78, v90, v87
	v_lshl_add_u32 v78, v78, 1, 0
	ds_read_b128 v[78:81], v78
	s_waitcnt lgkmcnt(1)
	v_mfma_f32_16x16x32_bf16 v[50:53], v[58:61], v[54:57], v[50:53]
	v_add_u32_e32 v58, v90, v88
	v_lshl_add_u32 v58, v58, 1, 0
	ds_read_b128 v[58:61], v58
	s_waitcnt lgkmcnt(1)
	v_mfma_f32_16x16x32_bf16 v[70:73], v[78:81], v[54:57], v[70:73]
	v_add_u32_e32 v78, v90, v89
	v_lshl_add_u32 v78, v78, 1, 0
	ds_read_b128 v[78:81], v78
	s_waitcnt lgkmcnt(1)
	v_mfma_f32_16x16x32_bf16 v[58:61], v[58:61], v[54:57], v[74:77]
	s_nop 2
	v_or_b32_e32 v74, 64, v0
	v_cmp_le_i32_e32 vcc, v74, v28
	v_or_b32_e32 v75, 0x41, v0
	s_waitcnt lgkmcnt(0)
	v_mfma_f32_16x16x32_bf16 v[30:33], v[78:81], v[54:57], v[30:33]
	s_waitcnt vmcnt(10)
	v_cndmask_b32_e32 v66, 0, v66, vcc
	v_cmp_le_i32_e32 vcc, v75, v28
	v_or_b32_e32 v75, 0x42, v0
	v_add_u32_e32 v54, v74, v83
	v_cndmask_b32_e32 v67, 0, v67, vcc
	v_cmp_le_i32_e32 vcc, v75, v28
	v_or_b32_e32 v75, 0x43, v0
	v_lshl_add_u32 v54, v54, 1, 0
	v_cndmask_b32_e32 v68, 0, v68, vcc
	v_cmp_le_i32_e32 vcc, v75, v28
	v_or_b32_e32 v75, 0x44, v0
	s_nop 0
	v_cndmask_b32_e32 v69, 0, v69, vcc
	v_cmp_le_i32_e32 vcc, v75, v28
	s_nop 1
	v_cndmask_b32_e32 v75, 0, v62, vcc
	v_or_b32_e32 v62, 0x45, v0
	v_cmp_le_i32_e32 vcc, v62, v28
	v_or_b32_e32 v62, 0x46, v0
	s_nop 0
	v_cndmask_b32_e32 v76, 0, v63, vcc
	v_cmp_le_i32_e32 vcc, v62, v28
	v_or_b32_e32 v62, 0x47, v0
	s_nop 0
	v_cndmask_b32_e32 v77, 0, v64, vcc
	v_cmp_le_i32_e32 vcc, v62, v28
	v_cvt_pk_bf16_f32 v62, v66, v67
	v_mad_u32_u24 v66, v82, s5, v74
	v_lshl_add_u32 v66, v66, 1, 0
	v_cndmask_b32_e32 v65, 0, v65, vcc
	v_cvt_pk_bf16_f32 v63, v68, v69
	v_cvt_pk_bf16_f32 v64, v75, v76
	v_cvt_pk_bf16_f32 v65, v77, v65
	ds_read_b128 v[66:69], v66
	ds_read_b128 v[54:57], v54
	s_waitcnt lgkmcnt(1)
	v_mfma_f32_16x16x32_bf16 v[34:37], v[66:69], v[62:65], v[34:37]
	v_add_u32_e32 v66, v74, v84
	v_lshl_add_u32 v66, v66, 1, 0
	ds_read_b128 v[66:69], v66
	s_waitcnt lgkmcnt(1)
; #define LAS __attribute__((address_space(3)))
; DEV float bflo(unsigned u) { return __uint_as_float(u << 16); }
; DEV float bfhi(unsigned u) { return __uint_as_float(u & 0xffff0000u); }
; DEV unsigned cvt_pk_bf16(float lo, float hi) { unsigned r; asm volatile("v_cvt_pk_bf16_f32 %0, %1, %2" : "=v"(r) : "v"(lo), "v"(hi)); return r; }
; DEV u32x4 pack8(const float (&f)[8]) { u32x4 w; w.x = cvt_pk_bf16(f[0], f[1]); w.y = cvt_pk_bf16(f[2], f[3]); w.z = cvt_pk_bf16(f[4], f[5]); w.w = cvt_pk_bf16(f[6], f[7]); return w; }
; DEV void sgu_item(LAS unsigned char* lds, const bf16_t* P, const bf16_t* VN, const float* sgu_w, const float* sgu_b, bf16_t* OC, int item) {
;     ...
; #pragma unroll
;     for (int ks = 0; ks < 4; ++ks) { const int s0 = ks * 32 + g4 * 8;
;         float wf[8] = {wa[ks][0], wa[ks][1], wa[ks][2], wa[ks][3], wb[ks][0], wb[ks][1], wb[ks][2], wb[ks][3]};
; #pragma unroll
;         for (int j = 0; j < 8; ++j) if (s0 + j > t) wf[j] = 0.f;
;         const bf16x8 wfr = as_bf16x8(pack8(wf));
; #pragma unroll
;         for (int n = 0; n < 8; ++n) { const bf16x8 vf = *(const LAS bf16x8*)(lds + ((n * 16 + fr) * 136 + s0) * 2);
;             acc[n] = __builtin_amdgcn_mfma_f32_16x16x32_bf16(vf, wfr, acc[n], 0, 0, 0); } }
; #pragma unroll
;     for (int n = 0; n < 8; ++n) { const int c = g * 128 + n * 16 + g4 * 4;
;         u32x2 w; w.x = cvt_pk_bf16(bflo(uu[n].x) * (acc[n][0] + bias), bfhi(uu[n].x) * (acc[n][1] + bias)); w.y = cvt_pk_bf16(bflo(uu[n].y) * (acc[n][2] + bias), bfhi(uu[n].y) * (acc[n][3] + bias));
	v_mfma_f32_16x16x32_bf16 v[38:41], v[54:57], v[62:65], v[38:41]
	v_add_u32_e32 v54, v74, v85
	v_lshl_add_u32 v54, v54, 1, 0
	ds_read_b128 v[54:57], v54
	s_waitcnt lgkmcnt(1)
	v_mfma_f32_16x16x32_bf16 v[42:45], v[66:69], v[62:65], v[42:45]
	v_add_u32_e32 v66, v74, v86
	v_lshl_add_u32 v66, v66, 1, 0
	ds_read_b128 v[66:69], v66
	s_waitcnt lgkmcnt(1)
	v_mfma_f32_16x16x32_bf16 v[46:49], v[54:57], v[62:65], v[46:49]
	v_add_u32_e32 v54, v74, v87
	v_lshl_add_u32 v54, v54, 1, 0
	ds_read_b128 v[54:57], v54
	s_waitcnt lgkmcnt(1)
	v_mfma_f32_16x16x32_bf16 v[50:53], v[66:69], v[62:65], v[50:53]
	v_add_u32_e32 v66, v74, v88
	v_lshl_add_u32 v66, v66, 1, 0
	ds_read_b128 v[66:69], v66
	s_waitcnt lgkmcnt(1)
	v_mfma_f32_16x16x32_bf16 v[54:57], v[54:57], v[62:65], v[70:73]
	s_nop 2
	v_add_u32_e32 v70, v74, v89
	v_lshl_add_u32 v70, v70, 1, 0
	ds_read_b128 v[70:73], v70
	s_waitcnt lgkmcnt(1)
	v_mfma_f32_16x16x32_bf16 v[58:61], v[66:69], v[62:65], v[58:61]
	v_or_b32_e32 v66, 0x60, v0
	v_cmp_le_i32_e32 vcc, v66, v28
	v_or_b32_e32 v67, 0x61, v0
	s_waitcnt lgkmcnt(0)
	v_mfma_f32_16x16x32_bf16 v[30:33], v[70:73], v[62:65], v[30:33]
	s_waitcnt vmcnt(8)
	v_cndmask_b32_e32 v6, 0, v6, vcc
	v_cmp_le_i32_e32 vcc, v67, v28
	v_or_b32_e32 v67, 0x62, v0
	s_nop 0
	v_cndmask_b32_e32 v7, 0, v7, vcc
	v_cmp_le_i32_e32 vcc, v67, v28
	v_or_b32_e32 v67, 0x63, v0
	s_nop 0
	v_cndmask_b32_e32 v8, 0, v8, vcc
	v_cmp_le_i32_e32 vcc, v67, v28
	v_or_b32_e32 v67, 0x64, v0
	s_nop 0
	v_cndmask_b32_e32 v9, 0, v9, vcc
	v_cmp_le_i32_e32 vcc, v67, v28
	s_nop 1
	v_cndmask_b32_e32 v67, 0, v2, vcc
	v_or_b32_e32 v2, 0x65, v0
	v_cmp_le_i32_e32 vcc, v2, v28
	v_or_b32_e32 v2, 0x66, v0
	s_nop 0
	v_cndmask_b32_e32 v68, 0, v3, vcc
	v_cmp_le_i32_e32 vcc, v2, v28
	v_or_b32_e32 v2, 0x67, v0
	v_or_b32_e32 v0, s4, v0
	v_cndmask_b32_e32 v69, 0, v4, vcc
	v_cmp_le_i32_e32 vcc, v2, v28
	v_cvt_pk_bf16_f32 v2, v6, v7
	v_mad_u32_u24 v6, v82, s5, v66
	v_lshl_add_u32 v6, v6, 1, 0
	v_cndmask_b32_e32 v5, 0, v5, vcc
	v_cvt_pk_bf16_f32 v3, v8, v9
	v_cvt_pk_bf16_f32 v4, v67, v68
	v_cvt_pk_bf16_f32 v5, v69, v5
	ds_read_b128 v[6:9], v6
	v_add_u32_e32 v28, v66, v83
	v_lshl_add_u32 v28, v28, 1, 0
	ds_read_b128 v[62:65], v28
	v_add_u32_e32 v28, v66, v84
	v_lshl_add_u32 v28, v28, 1, 0
	s_waitcnt lgkmcnt(1)
	v_mfma_f32_16x16x32_bf16 v[6:9], v[6:9], v[2:5], v[34:37]
	s_nop 2
	ds_read_b128 v[34:37], v28
	v_add_u32_e32 v28, v66, v85
	v_lshl_add_u32 v28, v28, 1, 0
	s_waitcnt lgkmcnt(1)
	v_mfma_f32_16x16x32_bf16 v[38:41], v[62:65], v[2:5], v[38:41]
	ds_read_b128 v[62:65], v28
	v_add_u32_e32 v28, v66, v86
	v_lshl_add_u32 v28, v28, 1, 0
	s_waitcnt lgkmcnt(1)
	v_mfma_f32_16x16x32_bf16 v[34:37], v[34:37], v[2:5], v[42:45]
	v_add_f32_e32 v6, v29, v6
	s_nop 1
	ds_read_b128 v[42:45], v28
	v_add_u32_e32 v28, v66, v87
	v_lshl_add_u32 v28, v28, 1, 0
	s_waitcnt lgkmcnt(1)
	v_mfma_f32_16x16x32_bf16 v[46:49], v[62:65], v[2:5], v[46:49]
	ds_read_b128 v[62:65], v28
	v_add_u32_e32 v28, v66, v88
	v_lshl_add_u32 v28, v28, 1, 0
	s_waitcnt lgkmcnt(1)
	v_mfma_f32_16x16x32_bf16 v[42:45], v[42:45], v[2:5], v[50:53]
	v_add_f32_e32 v7, v29, v7
	s_nop 1
	ds_read_b128 v[50:53], v28
	v_add_u32_e32 v28, v66, v89
	v_lshl_add_u32 v28, v28, 1, 0
	s_waitcnt lgkmcnt(1)
	v_mfma_f32_16x16x32_bf16 v[54:57], v[62:65], v[2:5], v[54:57]
	ds_read_b128 v[62:65], v28
	s_waitcnt vmcnt(3)
; DEV float bflo(unsigned u) { return __uint_as_float(u << 16); }
; DEV float bfhi(unsigned u) { return __uint_as_float(u & 0xffff0000u); }
; DEV unsigned cvt_pk_bf16(float lo, float hi) { unsigned r; asm volatile("v_cvt_pk_bf16_f32 %0, %1, %2" : "=v"(r) : "v"(lo), "v"(hi)); return r; }
; DEV void sgu_item(LAS unsigned char* lds, const bf16_t* P, const bf16_t* VN, const float* sgu_w, const float* sgu_b, bf16_t* OC, int item) {
;     ...
; #pragma unroll
;     for (int n = 0; n < 8; ++n) { const int c = g * 128 + n * 16 + g4 * 4;
;         u32x2 w; w.x = cvt_pk_bf16(bflo(uu[n].x) * (acc[n][0] + bias), bfhi(uu[n].x) * (acc[n][1] + bias)); w.y = cvt_pk_bf16(bflo(uu[n].y) * (acc[n][2] + bias), bfhi(uu[n].y) * (acc[n][3] + bias));
;         *(u32x2*)(OC + tok * 1024 + c) = w; }
;     __syncthreads();
	v_lshlrev_b32_e32 v28, 16, v26
	v_and_b32_e32 v26, 0xffff0000, v26
	v_mul_f32_e32 v6, v6, v28
	v_mul_f32_e32 v7, v7, v26
	v_cvt_pk_bf16_f32 v6, v6, v7
	v_lshlrev_b32_e32 v7, 16, v27
	v_add_f32_e32 v8, v29, v8
	v_mul_f32_e32 v7, v8, v7
	v_and_b32_e32 v8, 0xffff0000, v27
	v_add_f32_e32 v9, v29, v9
	v_mul_f32_e32 v8, v9, v8
	v_cvt_pk_bf16_f32 v7, v7, v8
	v_lshl_add_u64 v[8:9], v[24:25], 0, v[0:1]
	global_store_dwordx2 v[8:9], v[6:7], off
	v_lshlrev_b32_e32 v0, 16, v22
	v_add_f32_e32 v6, v29, v38
	v_mul_f32_e32 v0, v6, v0
	v_and_b32_e32 v6, 0xffff0000, v22
	v_add_f32_e32 v7, v29, v39
	v_mul_f32_e32 v6, v7, v6
	v_cvt_pk_bf16_f32 v6, v0, v6
	v_lshlrev_b32_e32 v0, 16, v23
	v_add_f32_e32 v7, v29, v40
	v_mul_f32_e32 v0, v7, v0
	v_and_b32_e32 v7, 0xffff0000, v23
	v_add_f32_e32 v22, v29, v41
	v_mul_f32_e32 v7, v22, v7
	v_cvt_pk_bf16_f32 v7, v0, v7
	global_store_dwordx2 v[8:9], v[6:7], off offset:32
	v_lshlrev_b32_e32 v0, 16, v20
	v_add_f32_e32 v6, v29, v34
	v_mul_f32_e32 v0, v6, v0
	v_and_b32_e32 v6, 0xffff0000, v20
	v_add_f32_e32 v7, v29, v35
	v_mul_f32_e32 v6, v7, v6
	v_cvt_pk_bf16_f32 v6, v0, v6
	v_lshlrev_b32_e32 v0, 16, v21
	v_add_f32_e32 v7, v29, v36
	v_mul_f32_e32 v0, v7, v0
	v_and_b32_e32 v7, 0xffff0000, v21
	v_add_f32_e32 v20, v29, v37
	v_mul_f32_e32 v7, v20, v7
	v_cvt_pk_bf16_f32 v7, v0, v7
	global_store_dwordx2 v[8:9], v[6:7], off offset:64
	v_lshlrev_b32_e32 v0, 16, v18
	v_add_f32_e32 v6, v29, v46
	v_mul_f32_e32 v0, v6, v0
	v_and_b32_e32 v6, 0xffff0000, v18
	v_add_f32_e32 v7, v29, v47
	v_mul_f32_e32 v6, v7, v6
	v_cvt_pk_bf16_f32 v6, v0, v6
	v_lshlrev_b32_e32 v0, 16, v19
	v_add_f32_e32 v7, v29, v48
	v_mul_f32_e32 v0, v7, v0
	v_and_b32_e32 v7, 0xffff0000, v19
	v_add_f32_e32 v18, v29, v49
	v_mul_f32_e32 v7, v18, v7
	v_cvt_pk_bf16_f32 v7, v0, v7
	global_store_dwordx2 v[8:9], v[6:7], off offset:96
	v_lshlrev_b32_e32 v0, 16, v16
	v_add_f32_e32 v6, v29, v42
	v_mul_f32_e32 v0, v6, v0
	v_and_b32_e32 v6, 0xffff0000, v16
	v_add_f32_e32 v7, v29, v43
	v_mul_f32_e32 v6, v7, v6
	v_cvt_pk_bf16_f32 v6, v0, v6
	v_lshlrev_b32_e32 v0, 16, v17
	v_add_f32_e32 v7, v29, v44
	v_mul_f32_e32 v0, v7, v0
	v_and_b32_e32 v7, 0xffff0000, v17
	v_add_f32_e32 v16, v29, v45
	v_mul_f32_e32 v7, v16, v7
	v_cvt_pk_bf16_f32 v7, v0, v7
	global_store_dwordx2 v[8:9], v[6:7], off offset:128
	s_waitcnt vmcnt(7)
	v_lshlrev_b32_e32 v0, 16, v14
	v_add_f32_e32 v6, v29, v54
	v_mul_f32_e32 v0, v6, v0
	v_and_b32_e32 v6, 0xffff0000, v14
	v_add_f32_e32 v7, v29, v55
	s_waitcnt lgkmcnt(1)
	v_mfma_f32_16x16x32_bf16 v[50:53], v[50:53], v[2:5], v[58:61]
	v_mul_f32_e32 v6, v7, v6
	v_cvt_pk_bf16_f32 v6, v0, v6
	v_lshlrev_b32_e32 v0, 16, v15
	v_add_f32_e32 v7, v29, v56
	v_mul_f32_e32 v0, v7, v0
	v_and_b32_e32 v7, 0xffff0000, v15
	v_add_f32_e32 v14, v29, v57
	v_mul_f32_e32 v7, v14, v7
	v_cvt_pk_bf16_f32 v7, v0, v7
	global_store_dwordx2 v[8:9], v[6:7], off offset:160
	s_waitcnt vmcnt(7)
	v_lshlrev_b32_e32 v0, 16, v12
	v_add_f32_e32 v6, v29, v50
	v_mul_f32_e32 v0, v6, v0
	v_and_b32_e32 v6, 0xffff0000, v12
	v_add_f32_e32 v7, v29, v51
	s_waitcnt lgkmcnt(0)
	v_mfma_f32_16x16x32_bf16 v[2:5], v[62:65], v[2:5], v[30:33]
	v_mul_f32_e32 v6, v7, v6
	v_cvt_pk_bf16_f32 v6, v0, v6
	v_lshlrev_b32_e32 v0, 16, v13
	v_add_f32_e32 v7, v29, v52
	v_mul_f32_e32 v0, v7, v0
	v_and_b32_e32 v7, 0xffff0000, v13
	v_add_f32_e32 v12, v29, v53
	v_mul_f32_e32 v7, v12, v7
	v_cvt_pk_bf16_f32 v7, v0, v7
	s_waitcnt vmcnt(6)
	v_lshlrev_b32_e32 v0, 16, v10
	v_add_f32_e32 v2, v29, v2
	v_mul_f32_e32 v0, v2, v0
	v_and_b32_e32 v2, 0xffff0000, v10
	v_add_f32_e32 v3, v29, v3
	v_mul_f32_e32 v2, v3, v2
	global_store_dwordx2 v[8:9], v[6:7], off offset:192
	v_cvt_pk_bf16_f32 v2, v0, v2
	v_lshlrev_b32_e32 v0, 16, v11
	v_add_f32_e32 v3, v29, v4
	v_mul_f32_e32 v0, v3, v0
	v_and_b32_e32 v3, 0xffff0000, v11
	v_add_f32_e32 v4, v29, v5
	v_mul_f32_e32 v3, v4, v3
	v_cvt_pk_bf16_f32 v3, v0, v3
	global_store_dwordx2 v[8:9], v[2:3], off offset:224
	s_barrier
	s_mov_b64 s[4:5], 0
